# prologue fp8 row conversion: two rows in flight per wave, wave max via DPP and permlane swaps
# speedup vs baseline: 1.0001x; 1.0001x over previous
.LBB0_76:
	v_readfirstlane_b32 s12, v2
	v_mov_b32_e32 v79, 0
	s_add_u32 s13, s12, s14
	s_min_u32 s18, s12, s16
	s_lshl_b32 s20, s18, 12
	s_mov_b32 s21, 0
	v_lshl_add_u64 v[68:69], s[20:21], 0, v[4:5]
	global_load_dwordx4 v[14:17], v[68:69], off
	global_load_dwordx4 v[18:21], v[68:69], off offset:16
	global_load_dwordx4 v[22:25], v[68:69], off offset:32
	global_load_dwordx4 v[26:29], v[68:69], off offset:48
	s_min_u32 s18, s13, s16
	s_lshl_b32 s20, s18, 12
	s_mov_b32 s21, 0
	v_lshl_add_u64 v[68:69], s[20:21], 0, v[4:5]
	global_load_dwordx4 v[52:55], v[68:69], off
	global_load_dwordx4 v[56:59], v[68:69], off offset:16
	global_load_dwordx4 v[60:63], v[68:69], off offset:32
	global_load_dwordx4 v[64:67], v[68:69], off offset:48
	s_waitcnt vmcnt(7)
	v_max3_f32 v13, |v14|, 0, |v15|
	v_max3_f32 v13, v13, |v16|, |v17|
	s_waitcnt vmcnt(6)
	v_max3_f32 v13, v13, |v18|, |v19|
	v_max3_f32 v13, v13, |v20|, |v21|
	s_waitcnt vmcnt(5)
	v_max3_f32 v13, v13, |v22|, |v23|
	v_max3_f32 v13, v13, |v24|, |v25|
	s_waitcnt vmcnt(4)
	v_max3_f32 v13, v13, |v26|, |v27|
	v_max3_f32 v13, v13, |v28|, |v29|
	s_nop 1
	v_max_f32_dpp v13, v13, v13 quad_perm:[1,0,3,2] row_mask:0xf bank_mask:0xf
	s_nop 1
	v_max_f32_dpp v13, v13, v13 quad_perm:[2,3,0,1] row_mask:0xf bank_mask:0xf
	s_nop 1
	v_max_f32_dpp v13, v13, v13 row_half_mirror row_mask:0xf bank_mask:0xf
	s_nop 1
	v_max_f32_dpp v13, v13, v13 row_mirror row_mask:0xf bank_mask:0xf
	v_mov_b32_e32 v73, v13
	s_nop 1
	v_permlane16_swap_b32_e32 v73, v13
	v_max_f32_e32 v13, v13, v73
	v_mov_b32_e32 v73, v13
	s_nop 1
	v_permlane32_swap_b32_e32 v73, v13
	v_max_f32_e32 v13, v13, v73
	v_div_scale_f32 v34, s[0:1], v13, v13, s15
	v_rcp_f32_e32 v35, v34
	v_div_scale_f32 v36, vcc, s15, v13, s15
	v_cmp_lt_f32_e64 s[0:1], 0, v13
	v_fma_f32 v37, -v34, v35, 1.0
	v_fmac_f32_e32 v35, v37, v35
	v_mul_f32_e32 v37, v36, v35
	v_fma_f32 v38, -v34, v37, v36
	v_fmac_f32_e32 v37, v38, v35
	v_fma_f32 v34, -v34, v37, v36
	v_div_fmas_f32 v34, v34, v35, v37
	v_div_fixup_f32 v34, v34, v13, s15
	v_cndmask_b32_e64 v34, 1.0, v34, s[0:1]
	v_mov_b32_e32 v30, 0
	v_mov_b32_e32 v31, 0
	v_mov_b32_e32 v32, 0
	v_mov_b32_e32 v33, 0
	v_mul_f32_e32 v14, v14, v34
	v_mul_f32_e32 v15, v15, v34
	v_mul_f32_e32 v18, v18, v34
	v_mul_f32_e32 v19, v19, v34
	v_mul_f32_e32 v22, v22, v34
	v_mul_f32_e32 v23, v23, v34
	v_mul_f32_e32 v26, v26, v34
	v_mul_f32_e32 v27, v27, v34
	v_cvt_pk_fp8_f32 v30, v14, v15
	v_cvt_pk_fp8_f32 v31, v18, v19
	v_cvt_pk_fp8_f32 v32, v22, v23
	v_cvt_pk_fp8_f32 v33, v26, v27
	v_mul_f32_e32 v16, v16, v34
	v_mul_f32_e32 v17, v17, v34
	v_mul_f32_e32 v20, v20, v34
	v_mul_f32_e32 v21, v21, v34
	v_mul_f32_e32 v24, v24, v34
	v_mul_f32_e32 v25, v25, v34
	v_mul_f32_e32 v28, v28, v34
	v_mul_f32_e32 v29, v29, v34
	v_cvt_pk_fp8_f32 v30, v16, v17 op_sel:[0,0,1]
	v_cvt_pk_fp8_f32 v31, v20, v21 op_sel:[0,0,1]
	v_cvt_pk_fp8_f32 v32, v24, v25 op_sel:[0,0,1]
	v_cvt_pk_fp8_f32 v33, v28, v29 op_sel:[0,0,1]
	v_div_scale_f32 v74, s[18:19], s15, s15, v13
	v_rcp_f32_e32 v75, v74
	v_div_scale_f32 v76, vcc, v13, s15, v13
	v_fma_f32 v77, -v74, v75, 1.0
	v_fmac_f32_e32 v75, v77, v75
	v_mul_f32_e32 v77, v76, v75
	v_fma_f32 v78, -v74, v77, v76
	v_fmac_f32_e32 v77, v78, v75
	v_fma_f32 v74, -v74, v77, v76
	v_div_fmas_f32 v74, v74, v75, v77
	v_div_fixup_f32 v72, v74, s15, v13
	v_cndmask_b32_e64 v72, 1.0, v72, s[0:1]
.Lcvu_loop:
	s_lshl_b32 s20, s12, 10
	s_mov_b32 s21, 0
	v_lshl_add_u64 v[70:71], s[20:21], 0, v[6:7]
	global_store_dwordx4 v[70:71], v[30:33], off
	s_lshl_b32 s20, s12, 2
	s_add_u32 s20, s8, s20
	s_addc_u32 s21, s9, 0
	s_mov_b64 s[26:27], exec
	s_and_b64 exec, exec, s[4:5]
	global_store_dword v79, v72, s[20:21]
	s_mov_b64 exec, s[26:27]
	s_cmp_gt_u32 s13, s16
	s_cbranch_scc1 .Lcvu_exit
	s_add_u32 s12, s13, s14
	s_min_u32 s18, s12, s16
	s_lshl_b32 s20, s18, 12
	s_mov_b32 s21, 0
	v_lshl_add_u64 v[68:69], s[20:21], 0, v[4:5]
	global_load_dwordx4 v[14:17], v[68:69], off
	global_load_dwordx4 v[18:21], v[68:69], off offset:16
	global_load_dwordx4 v[22:25], v[68:69], off offset:32
	global_load_dwordx4 v[26:29], v[68:69], off offset:48
	s_waitcnt vmcnt(9)
	v_max3_f32 v13, |v52|, 0, |v53|
	v_max3_f32 v13, v13, |v54|, |v55|
	s_waitcnt vmcnt(8)
	v_max3_f32 v13, v13, |v56|, |v57|
	v_max3_f32 v13, v13, |v58|, |v59|
	s_waitcnt vmcnt(7)
	v_max3_f32 v13, v13, |v60|, |v61|
	v_max3_f32 v13, v13, |v62|, |v63|
	s_waitcnt vmcnt(6)
	v_max3_f32 v13, v13, |v64|, |v65|
	v_max3_f32 v13, v13, |v66|, |v67|
	s_nop 1
	v_max_f32_dpp v13, v13, v13 quad_perm:[1,0,3,2] row_mask:0xf bank_mask:0xf
	s_nop 1
	v_max_f32_dpp v13, v13, v13 quad_perm:[2,3,0,1] row_mask:0xf bank_mask:0xf
	s_nop 1
	v_max_f32_dpp v13, v13, v13 row_half_mirror row_mask:0xf bank_mask:0xf
	s_nop 1
	v_max_f32_dpp v13, v13, v13 row_mirror row_mask:0xf bank_mask:0xf
	v_mov_b32_e32 v73, v13
	s_nop 1
	v_permlane16_swap_b32_e32 v73, v13
	v_max_f32_e32 v13, v13, v73
	v_mov_b32_e32 v73, v13
	s_nop 1
	v_permlane32_swap_b32_e32 v73, v13
	v_max_f32_e32 v13, v13, v73
	v_div_scale_f32 v34, s[0:1], v13, v13, s15
	v_rcp_f32_e32 v35, v34
	v_div_scale_f32 v36, vcc, s15, v13, s15
	v_cmp_lt_f32_e64 s[0:1], 0, v13
	v_fma_f32 v37, -v34, v35, 1.0
	v_fmac_f32_e32 v35, v37, v35
	v_mul_f32_e32 v37, v36, v35
	v_fma_f32 v38, -v34, v37, v36
	v_fmac_f32_e32 v37, v38, v35
	v_fma_f32 v34, -v34, v37, v36
	v_div_fmas_f32 v34, v34, v35, v37
	v_div_fixup_f32 v34, v34, v13, s15
	v_cndmask_b32_e64 v34, 1.0, v34, s[0:1]
	v_mov_b32_e32 v30, 0
	v_mov_b32_e32 v31, 0
	v_mov_b32_e32 v32, 0
	v_mov_b32_e32 v33, 0
	v_mul_f32_e32 v52, v52, v34
	v_mul_f32_e32 v53, v53, v34
	v_mul_f32_e32 v56, v56, v34
	v_mul_f32_e32 v57, v57, v34
	v_mul_f32_e32 v60, v60, v34
	v_mul_f32_e32 v61, v61, v34
	v_mul_f32_e32 v64, v64, v34
	v_mul_f32_e32 v65, v65, v34
	v_cvt_pk_fp8_f32 v30, v52, v53
	v_cvt_pk_fp8_f32 v31, v56, v57
	v_cvt_pk_fp8_f32 v32, v60, v61
	v_cvt_pk_fp8_f32 v33, v64, v65
	v_mul_f32_e32 v54, v54, v34
	v_mul_f32_e32 v55, v55, v34
	v_mul_f32_e32 v58, v58, v34
	v_mul_f32_e32 v59, v59, v34
	v_mul_f32_e32 v62, v62, v34
	v_mul_f32_e32 v63, v63, v34
	v_mul_f32_e32 v66, v66, v34
	v_mul_f32_e32 v67, v67, v34
	v_cvt_pk_fp8_f32 v30, v54, v55 op_sel:[0,0,1]
	v_cvt_pk_fp8_f32 v31, v58, v59 op_sel:[0,0,1]
	v_cvt_pk_fp8_f32 v32, v62, v63 op_sel:[0,0,1]
	v_cvt_pk_fp8_f32 v33, v66, v67 op_sel:[0,0,1]
	v_div_scale_f32 v74, s[18:19], s15, s15, v13
	v_rcp_f32_e32 v75, v74
	v_div_scale_f32 v76, vcc, v13, s15, v13
	v_fma_f32 v77, -v74, v75, 1.0
	v_fmac_f32_e32 v75, v77, v75
	v_mul_f32_e32 v77, v76, v75
	v_fma_f32 v78, -v74, v77, v76
	v_fmac_f32_e32 v77, v78, v75
	v_fma_f32 v74, -v74, v77, v76
	v_div_fmas_f32 v74, v74, v75, v77
	v_div_fixup_f32 v72, v74, s15, v13
	v_cndmask_b32_e64 v72, 1.0, v72, s[0:1]
	s_lshl_b32 s20, s13, 10
	s_mov_b32 s21, 0
	v_lshl_add_u64 v[70:71], s[20:21], 0, v[6:7]
	global_store_dwordx4 v[70:71], v[30:33], off
	s_lshl_b32 s20, s13, 2
	s_add_u32 s20, s8, s20
	s_addc_u32 s21, s9, 0
	s_mov_b64 s[26:27], exec
	s_and_b64 exec, exec, s[4:5]
	global_store_dword v79, v72, s[20:21]
	s_mov_b64 exec, s[26:27]
	s_cmp_gt_u32 s12, s16
	s_cbranch_scc1 .Lcvu_exit
	s_add_u32 s13, s12, s14
	s_min_u32 s18, s13, s16
	s_lshl_b32 s20, s18, 12
	s_mov_b32 s21, 0
	v_lshl_add_u64 v[68:69], s[20:21], 0, v[4:5]
	global_load_dwordx4 v[52:55], v[68:69], off
	global_load_dwordx4 v[56:59], v[68:69], off offset:16
	global_load_dwordx4 v[60:63], v[68:69], off offset:32
	global_load_dwordx4 v[64:67], v[68:69], off offset:48
	s_waitcnt vmcnt(9)
	v_max3_f32 v13, |v14|, 0, |v15|
	v_max3_f32 v13, v13, |v16|, |v17|
	s_waitcnt vmcnt(8)
	v_max3_f32 v13, v13, |v18|, |v19|
	v_max3_f32 v13, v13, |v20|, |v21|
	s_waitcnt vmcnt(7)
	v_max3_f32 v13, v13, |v22|, |v23|
	v_max3_f32 v13, v13, |v24|, |v25|
	s_waitcnt vmcnt(6)
	v_max3_f32 v13, v13, |v26|, |v27|
	v_max3_f32 v13, v13, |v28|, |v29|
	s_nop 1
	v_max_f32_dpp v13, v13, v13 quad_perm:[1,0,3,2] row_mask:0xf bank_mask:0xf
	s_nop 1
	v_max_f32_dpp v13, v13, v13 quad_perm:[2,3,0,1] row_mask:0xf bank_mask:0xf
	s_nop 1
	v_max_f32_dpp v13, v13, v13 row_half_mirror row_mask:0xf bank_mask:0xf
	s_nop 1
	v_max_f32_dpp v13, v13, v13 row_mirror row_mask:0xf bank_mask:0xf
	v_mov_b32_e32 v73, v13
	s_nop 1
	v_permlane16_swap_b32_e32 v73, v13
	v_max_f32_e32 v13, v13, v73
	v_mov_b32_e32 v73, v13
	s_nop 1
	v_permlane32_swap_b32_e32 v73, v13
	v_max_f32_e32 v13, v13, v73
	v_div_scale_f32 v34, s[0:1], v13, v13, s15
	v_rcp_f32_e32 v35, v34
	v_div_scale_f32 v36, vcc, s15, v13, s15
	v_cmp_lt_f32_e64 s[0:1], 0, v13
	v_fma_f32 v37, -v34, v35, 1.0
	v_fmac_f32_e32 v35, v37, v35
	v_mul_f32_e32 v37, v36, v35
	v_fma_f32 v38, -v34, v37, v36
	v_fmac_f32_e32 v37, v38, v35
	v_fma_f32 v34, -v34, v37, v36
	v_div_fmas_f32 v34, v34, v35, v37
	v_div_fixup_f32 v34, v34, v13, s15
	v_cndmask_b32_e64 v34, 1.0, v34, s[0:1]
	v_mov_b32_e32 v30, 0
	v_mov_b32_e32 v31, 0
	v_mov_b32_e32 v32, 0
	v_mov_b32_e32 v33, 0
	v_mul_f32_e32 v14, v14, v34
	v_mul_f32_e32 v15, v15, v34
	v_mul_f32_e32 v18, v18, v34
	v_mul_f32_e32 v19, v19, v34
	v_mul_f32_e32 v22, v22, v34
	v_mul_f32_e32 v23, v23, v34
	v_mul_f32_e32 v26, v26, v34
	v_mul_f32_e32 v27, v27, v34
	v_cvt_pk_fp8_f32 v30, v14, v15
	v_cvt_pk_fp8_f32 v31, v18, v19
	v_cvt_pk_fp8_f32 v32, v22, v23
	v_cvt_pk_fp8_f32 v33, v26, v27
	v_mul_f32_e32 v16, v16, v34
	v_mul_f32_e32 v17, v17, v34
	v_mul_f32_e32 v20, v20, v34
	v_mul_f32_e32 v21, v21, v34
	v_mul_f32_e32 v24, v24, v34
	v_mul_f32_e32 v25, v25, v34
	v_mul_f32_e32 v28, v28, v34
	v_mul_f32_e32 v29, v29, v34
	v_cvt_pk_fp8_f32 v30, v16, v17 op_sel:[0,0,1]
	v_cvt_pk_fp8_f32 v31, v20, v21 op_sel:[0,0,1]
	v_cvt_pk_fp8_f32 v32, v24, v25 op_sel:[0,0,1]
	v_cvt_pk_fp8_f32 v33, v28, v29 op_sel:[0,0,1]
	v_div_scale_f32 v74, s[18:19], s15, s15, v13
	v_rcp_f32_e32 v75, v74
	v_div_scale_f32 v76, vcc, v13, s15, v13
	v_fma_f32 v77, -v74, v75, 1.0
	v_fmac_f32_e32 v75, v77, v75
	v_mul_f32_e32 v77, v76, v75
	v_fma_f32 v78, -v74, v77, v76
	v_fmac_f32_e32 v77, v78, v75
	v_fma_f32 v74, -v74, v77, v76
	v_div_fmas_f32 v74, v74, v75, v77
	v_div_fixup_f32 v72, v74, s15, v13
	v_cndmask_b32_e64 v72, 1.0, v72, s[0:1]
	s_branch .Lcvu_loop
.Lcvu_exit:
	s_waitcnt vmcnt(0)
.LBB0_78:
	s_or_b64 exec, exec, s[6:7]
	v_mov_b32_e32 v1, v179
	v_mov_b32_e32 v2, v179
	v_readlane_b32 s0, v252, 7
	v_ashrrev_i32_e32 v2, 6, v2
	s_nop 0
	v_add_u32_e32 v2, s0, v2
	s_mov_b32 s0, 0x10000
	v_cmp_gt_i32_e32 vcc, s0, v2
	s_and_saveexec_b64 s[6:7], vcc
	s_cbranch_execz .LBB0_83
	v_readlane_b32 s0, v252, 0
	v_mbcnt_lo_u32_b32 v3, -1, 0
	v_readlane_b32 s1, v252, 1
	v_mbcnt_hi_u32_b32 v3, -1, v3
	s_load_dword s10, s[0:1], 0x0
	s_load_dword s11, s[0:1], 0x10
	v_and_b32_e32 v1, 63, v1
	v_and_b32_e32 v8, 64, v3
	v_lshlrev_b32_e32 v6, 4, v1
	v_lshlrev_b32_e32 v4, 6, v1
	v_add_u32_e32 v12, 64, v8
	v_cmp_eq_u32_e64 s[4:5], 0, v1
	v_xor_b32_e32 v1, 32, v3
	v_mov_b32_e32 v7, 0
	v_cmp_lt_i32_e32 vcc, v1, v12
	v_xor_b32_e32 v8, 16, v3
	s_add_u32 s8, s24, 0xaa7d700
	v_mov_b32_e32 v5, v7
	v_lshl_add_u64 v[6:7], s[24:25], 0, v[6:7]
	s_mov_b64 s[0:1], 0x6a3d700
	v_cndmask_b32_e32 v1, v3, v1, vcc
	v_cmp_lt_i32_e32 vcc, v8, v12
	v_xor_b32_e32 v9, 8, v3
	s_addc_u32 s9, s25, 0
	v_lshl_add_u64 v[6:7], v[6:7], 0, s[0:1]
	s_waitcnt lgkmcnt(0)
	s_lshr_b32 s0, s11, 16
	v_cndmask_b32_e32 v8, v3, v8, vcc
	v_cmp_lt_i32_e32 vcc, v9, v12
	v_xor_b32_e32 v10, 4, v3
	s_cmp_lg_u32 s0, 0
	v_cndmask_b32_e32 v9, v3, v9, vcc
	v_cmp_lt_i32_e32 vcc, v10, v12
	v_xor_b32_e32 v11, 2, v3
	s_cselect_b64 s[0:1], -1, 0
	v_cndmask_b32_e32 v10, v3, v10, vcc
	v_cmp_lt_i32_e32 vcc, v11, v12
	v_xor_b32_e32 v13, 1, v3
	s_cmp_lg_u64 s[0:1], 0
	v_cndmask_b32_e32 v11, v3, v11, vcc
	v_cmp_lt_i32_e32 vcc, v13, v12
	s_addc_u32 s0, s10, 0
	v_lshl_add_u64 v[4:5], s[86:87], 0, v[4:5]
	v_cndmask_b32_e32 v3, v3, v13, vcc
	s_lshl_b32 s14, s0, 2
	v_lshlrev_b32_e32 v1, 2, v1
	v_lshlrev_b32_e32 v8, 2, v8
	v_lshlrev_b32_e32 v9, 2, v9
	v_lshlrev_b32_e32 v10, 2, v10
	v_lshlrev_b32_e32 v11, 2, v11
	v_lshlrev_b32_e32 v12, 2, v3
	s_mov_b64 s[10:11], 0
	s_mov_b32 s15, 0x43dc0000
	s_mov_b32 s16, 0xffff
	s_branch .LBB0_81

.Lcvv_exit:
	s_waitcnt vmcnt(0)
.LBB0_83:
	s_or_b64 exec, exec, s[6:7]
	s_cmp_lt_i32 s93, 2
	s_cbranch_scc1 .LBB0_150
	s_cmp_lg_u32 s92, 0
	s_cbranch_scc0 .LBB0_96
	s_waitcnt vmcnt(0)
	s_barrier
	s_mov_b64 s[0:1], exec
	v_readlane_b32 s4, v252, 2
	v_readlane_b32 s5, v252, 3
	s_and_b64 s[4:5], s[0:1], s[4:5]
	s_mov_b64 exec, s[4:5]
	s_cbranch_execz .LBB0_138
	s_add_i32 s4, 0, 0x127e0
	v_mov_b32_e32 v1, s4
	s_waitcnt vmcnt(0) expcnt(0) lgkmcnt(0)
	ds_read_b32 v3, v1
	s_add_i32 s4, 0, 0x127e4
	v_mov_b32_e32 v1, s4
	ds_read_b32 v1, v1
	s_waitcnt lgkmcnt(1)
	v_cmp_ne_u32_e32 vcc, 0, v3
	s_cbranch_vccnz .LBB0_102
	v_readlane_b32 s12, v252, 4
	v_readlane_b32 s13, v252, 5
	s_add_u32 s4, s12, 0x1000
	s_addc_u32 s5, s13, 0
	s_add_u32 s6, s12, 0x1100
	s_addc_u32 s7, s13, 0
	s_add_u32 s8, s12, 0x1200
	s_addc_u32 s9, s13, 0
	s_add_u32 s10, s12, 0x1300
	s_addc_u32 s11, s13, 0
	s_mul_i32 s20, s95, s31
	s_add_u32 s12, s12, 0x1400
	s_mul_i32 s20, s20, s94
	s_addc_u32 s13, s13, 0
	s_mov_b32 s21, 1
	v_mov_b32_e32 v17, 0
	s_branch .LBB0_89
